# seam 2/3 waits: first poll(s) and the L1 invalidate issued together (one round trip instead of three); rest as v149
# speedup vs baseline: 1.0049x; 1.0046x over previous
; __device__ __forceinline__ u32x4 pack8(const f32x4 a, const f32x4 b) { u32x4 w; w.x = cvt_pk_bf16(a[0], a[1]); w.y = cvt_pk_bf16(a[2], a[3]); w.z = cvt_pk_bf16(b[0], b[1]); w.w = cvt_pk_bf16(b[2], b[3]); return w; }
; __device__ __forceinline__ int lane_id() { int l; asm volatile("v_mbcnt_lo_u32_b32 %0, -1, 0\n\tv_mbcnt_hi_u32_b32 %0, -1, %0" : "=v"(l)); return l; }
; __device__ __forceinline__ unsigned xb_ld(unsigned* p)              { return __hip_atomic_load(p, __ATOMIC_RELAXED, __HIP_MEMORY_SCOPE_AGENT); }
; #define XB_SPIN(cond, bar) do { unsigned _sp = 0; while (cond) { __builtin_amdgcn_s_sleep(1); \
;     if ((++_sp & 255u) == 0u) { if (xb_ld(&(bar)[XB_TMO])) break; if (_sp > XB_SPIN_CAP) { atomicAdd(&(bar)[XB_TMO], 1u); break; } } } } while (0)
;     __device__ __forceinline__ void operator()(const f32x4 (&acc)[2][2][4][2], const Unit& u, int wr, int wc, int fr, int fq) const {
;         const int row0 = u.pm * BM + wr * 64 + fr, col0 = u.pn * BM + wc * 32 + 8 * fq;
; #pragma unroll
;         for (int ai = 0; ai < 2; ++ai)
; #pragma unroll
;             for (int m = 0; m < 4; ++m) { bf16_t* rowp = O + (size_t)(row0 + ai * HALF + m * 16) * ldc + col0;
; #pragma unroll
;                 for (int bj = 0; bj < 2; ++bj) *(u32x4*)(rowp + bj * HALF) = pack8(acc[ai][bj][m][0], acc[ai][bj][m][1]); }
; __device__ __forceinline__ void xcd_wait2(const XcdBarrier& b, unsigned use, unsigned* obar, unsigned ouse) {
;     if (b.w0 != 0 && lane_id() == 0) {
;         unsigned* bar = b.bar;
;         XB_SPIN(xb_ld(&obar[XB_TOPGEN]) <= ouse, bar);
;         XB_SPIN(xb_ld(&bar[XB_TOPGEN]) <= use, bar);
;         __builtin_amdgcn_fence(__ATOMIC_ACQUIRE, "agent");
;         asm volatile("s_waitcnt vmcnt(0)" ::: "memory");
;     }
;     __syncthreads();
.LBB0_486:
	s_add_u32 s0, s34, s46
	s_addc_u32 s1, s35, 0
	s_add_u32 s2, s0, 0x13200000
	s_addc_u32 s3, s1, 0
	v_lshl_add_u32 v130, s12, 8, v129
	s_lshl_b32 s0, s91, 8
	s_or_b32 s97, s54, s0
	v_ashrrev_i32_e32 v131, 31, v130
	v_or_b32_e32 v132, s97, v128
	v_lshlrev_b64 v[128:129], 12, v[130:131]
	v_lshl_add_u64 v[128:129], s[2:3], 0, v[128:129]
	v_lshlrev_b32_e32 v168, 1, v132
	v_mov_b32_e32 v169, 0
	v_lshl_add_u64 v[128:129], v[128:129], 0, v[168:169]
	v_cvt_pk_bf16_f32 v120, v120, v121
	v_cvt_pk_bf16_f32 v121, v122, v123
	v_cvt_pk_bf16_f32 v122, v112, v113
	v_cvt_pk_bf16_f32 v123, v114, v115
	global_store_dwordx4 v[128:129], v[120:123], off
	v_cvt_pk_bf16_f32 v112, v124, v125
	v_cvt_pk_bf16_f32 v113, v126, v127
	v_cvt_pk_bf16_f32 v114, v116, v117
	v_cvt_pk_bf16_f32 v115, v118, v119
	global_store_dwordx4 v[128:129], v[112:115], off offset:256
	v_cvt_pk_bf16_f32 v104, v104, v105
	v_cvt_pk_bf16_f32 v105, v106, v107
	v_cvt_pk_bf16_f32 v106, v96, v97
	v_cvt_pk_bf16_f32 v107, v98, v99
	v_writelane_b32 v254, s0, 17
	s_nop 0
	v_or_b32_e32 v112, 16, v130
	v_ashrrev_i32_e32 v113, 31, v112
	v_lshlrev_b64 v[112:113], 12, v[112:113]
	v_lshl_add_u64 v[112:113], s[2:3], 0, v[112:113]
	v_lshl_add_u64 v[112:113], v[112:113], 0, v[168:169]
	global_store_dwordx4 v[112:113], v[104:107], off
	v_cvt_pk_bf16_f32 v96, v108, v109
	v_cvt_pk_bf16_f32 v97, v110, v111
	v_cvt_pk_bf16_f32 v98, v100, v101
	v_cvt_pk_bf16_f32 v99, v102, v103
	global_store_dwordx4 v[112:113], v[96:99], off offset:256
	v_cvt_pk_bf16_f32 v88, v88, v89
	v_cvt_pk_bf16_f32 v89, v90, v91
	v_cvt_pk_bf16_f32 v90, v80, v81
	v_cvt_pk_bf16_f32 v91, v82, v83
	s_mov_b32 s0, 0x80000
	s_nop 0
	v_or_b32_e32 v96, 32, v130
	v_ashrrev_i32_e32 v97, 31, v96
	v_lshlrev_b64 v[96:97], 12, v[96:97]
	v_lshl_add_u64 v[96:97], s[2:3], 0, v[96:97]
	v_lshl_add_u64 v[96:97], v[96:97], 0, v[168:169]
	global_store_dwordx4 v[96:97], v[88:91], off
	v_cvt_pk_bf16_f32 v80, v92, v93
	v_cvt_pk_bf16_f32 v81, v94, v95
	v_cvt_pk_bf16_f32 v82, v84, v85
	v_cvt_pk_bf16_f32 v83, v86, v87
	global_store_dwordx4 v[96:97], v[80:83], off offset:256
	v_cvt_pk_bf16_f32 v56, v56, v57
	v_cvt_pk_bf16_f32 v57, v58, v59
	v_cvt_pk_bf16_f32 v58, v48, v49
	v_cvt_pk_bf16_f32 v59, v50, v51
	s_mov_b64 s[36:37], 0x80000
	s_nop 0
	v_or_b32_e32 v80, 48, v130
	v_ashrrev_i32_e32 v81, 31, v80
	v_lshlrev_b64 v[80:81], 12, v[80:81]
	v_lshl_add_u64 v[80:81], s[2:3], 0, v[80:81]
	v_lshl_add_u64 v[80:81], v[80:81], 0, v[168:169]
	global_store_dwordx4 v[80:81], v[56:59], off
	v_cvt_pk_bf16_f32 v48, v60, v61
	v_cvt_pk_bf16_f32 v49, v62, v63
	v_cvt_pk_bf16_f32 v50, v52, v53
	v_cvt_pk_bf16_f32 v51, v54, v55
	v_add_co_u32_e32 v54, vcc, s0, v128
	global_store_dwordx4 v[80:81], v[48:51], off offset:256
	s_nop 0
	v_addc_co_u32_e32 v55, vcc, 0, v129, vcc
	v_cvt_pk_bf16_f32 v48, v76, v77
	v_cvt_pk_bf16_f32 v49, v78, v79
	v_lshl_add_u64 v[52:53], v[128:129], 0, s[36:37]
	v_cvt_pk_bf16_f32 v50, v68, v69
	v_cvt_pk_bf16_f32 v51, v70, v71
	global_store_dwordx4 v[54:55], v[48:51], off
	s_mov_b64 s[0:1], 0x90000
	s_nop 0
	v_cvt_pk_bf16_f32 v48, v72, v73
	v_cvt_pk_bf16_f32 v49, v74, v75
	v_cvt_pk_bf16_f32 v50, v64, v65
	v_cvt_pk_bf16_f32 v51, v66, v67
	global_store_dwordx4 v[52:53], v[48:51], off offset:256
	v_cvt_pk_bf16_f32 v44, v44, v45
	v_cvt_pk_bf16_f32 v45, v46, v47
	v_cvt_pk_bf16_f32 v46, v36, v37
	v_cvt_pk_bf16_f32 v47, v38, v39
	s_nop 1
	v_lshl_add_u64 v[48:49], v[128:129], 0, s[0:1]
	s_mov_b32 s0, 0x90000
	v_add_co_u32_e32 v36, vcc, s0, v128
	s_mov_b64 s[0:1], 0xa0000
	s_nop 0
	v_addc_co_u32_e32 v37, vcc, 0, v129, vcc
	global_store_dwordx4 v[36:37], v[44:47], off
	v_cvt_pk_bf16_f32 v36, v40, v41
	v_cvt_pk_bf16_f32 v37, v42, v43
	v_cvt_pk_bf16_f32 v38, v32, v33
	v_lshl_add_u64 v[32:33], v[128:129], 0, s[0:1]
	s_mov_b32 s0, 0xa0000
	v_cvt_pk_bf16_f32 v39, v34, v35
	global_store_dwordx4 v[48:49], v[36:39], off offset:256
	v_cvt_pk_bf16_f32 v28, v28, v29
	v_cvt_pk_bf16_f32 v29, v30, v31
	v_cvt_pk_bf16_f32 v30, v20, v21
	v_add_co_u32_e32 v20, vcc, s0, v128
	s_mov_b64 s[0:1], 0xb0000
	s_nop 0
	v_addc_co_u32_e32 v21, vcc, 0, v129, vcc
	v_cvt_pk_bf16_f32 v31, v22, v23
	global_store_dwordx4 v[20:21], v[28:31], off
	v_cvt_pk_bf16_f32 v20, v24, v25
	v_cvt_pk_bf16_f32 v21, v26, v27
	v_cvt_pk_bf16_f32 v22, v16, v17
	v_lshl_add_u64 v[16:17], v[128:129], 0, s[0:1]
	s_mov_b32 s0, 0xb0000
	v_cvt_pk_bf16_f32 v23, v18, v19
	global_store_dwordx4 v[32:33], v[20:23], off offset:256
	v_cvt_pk_bf16_f32 v12, v12, v13
	v_cvt_pk_bf16_f32 v13, v14, v15
	v_cvt_pk_bf16_f32 v14, v4, v5
	v_add_co_u32_e32 v4, vcc, s0, v128
	v_cvt_pk_bf16_f32 v15, v6, v7
	s_nop 1
	v_addc_co_u32_e32 v5, vcc, 0, v129, vcc
	global_store_dwordx4 v[4:5], v[12:15], off
	v_cvt_pk_bf16_f32 v4, v8, v9
	v_cvt_pk_bf16_f32 v5, v10, v11
	v_cvt_pk_bf16_f32 v6, v0, v1
	v_cvt_pk_bf16_f32 v7, v2, v3
	global_store_dwordx4 v[16:17], v[4:7], off offset:256
	s_waitcnt vmcnt(0)
	s_and_b64 vcc, exec, s[94:95]
	s_barrier
	s_cbranch_vccnz .LBB0_516
	v_mbcnt_lo_u32_b32 v0, -1, 0
	v_mbcnt_hi_u32_b32 v0, -1, v0
	s_nop 0
	v_cmp_eq_u32_e32 vcc, 0, v0
	s_and_saveexec_b64 s[14:15], vcc
	s_cbranch_execz .LBB0_515
	v_readlane_b32 s40, v254, 0
	s_xor_b32 s40, s40, 1
	s_mulk_i32 s40, 0x3600
	s_add_u32 s40, s34, s40
	s_addc_u32 s41, s35, 0
	v_mov_b32_e32 v0, 0x17000
	global_load_dword v2, v0, s[40:41] offset:1280 sc1
	v_readlane_b32 s38, v254, 19
	v_readlane_b32 s39, v254, 21
	s_add_i32 s38, s38, s39
	s_lshl_b32 s38, s38, 7
	s_add_u32 s38, s38, 0x7000
	v_mov_b32_e32 v0, s38
	global_load_dword v1, v0, s[52:53] sc1
	buffer_inv sc1
	s_waitcnt vmcnt(0)
	v_cmp_lt_u32_e32 vcc, 1, v2
	v_cmp_lt_u32_e64 s[38:39], 7, v1
	s_and_b64 vcc, vcc, s[38:39]
	s_cbranch_vccnz .LBB0_515
	v_readlane_b32 s0, v254, 0
	s_xor_b32 s0, s0, 1
	s_mulk_i32 s0, 0x3600
	s_add_u32 s0, s34, s0
	s_addc_u32 s1, s35, 0
	v_mov_b32_e32 v0, 0x17000
	global_load_dword v0, v0, s[0:1] offset:1280 sc1
	s_add_u32 s38, s0, 0x17500
	s_addc_u32 s39, s1, 0
	s_mov_b32 s0, 1
	s_waitcnt vmcnt(0)
	v_cmp_lt_u32_e32 vcc, 1, v0
	s_cbranch_vccnz .LBB0_501
	v_mov_b32_e32 v0, 0
	s_branch .LBB0_491

; __device__ __forceinline__ u32x4 pack8(const f32x4 a, const f32x4 b) { u32x4 w; w.x = cvt_pk_bf16(a[0], a[1]); w.y = cvt_pk_bf16(a[2], a[3]); w.z = cvt_pk_bf16(b[0], b[1]); w.w = cvt_pk_bf16(b[2], b[3]); return w; }
; __device__ __forceinline__ int lane_id() { int l; asm volatile("v_mbcnt_lo_u32_b32 %0, -1, 0\n\tv_mbcnt_hi_u32_b32 %0, -1, %0" : "=v"(l)); return l; }
; __device__ __forceinline__ unsigned xb_ld(unsigned* p)              { return __hip_atomic_load(p, __ATOMIC_RELAXED, __HIP_MEMORY_SCOPE_AGENT); }
; #define XB_SPIN(cond, bar) do { unsigned _sp = 0; while (cond) { __builtin_amdgcn_s_sleep(1); \
;     if ((++_sp & 255u) == 0u) { if (xb_ld(&(bar)[XB_TMO])) break; if (_sp > XB_SPIN_CAP) { atomicAdd(&(bar)[XB_TMO], 1u); break; } } } } while (0)
;     __device__ __forceinline__ void operator()(const f32x4 (&acc)[2][2][4][2], const Unit& u, int wr, int wc, int fr, int fq) const {
;         const int row0 = u.pm * BM + wr * 64 + fr, col0 = u.pn * BM + wc * 32 + 8 * fq;
; #pragma unroll
;         for (int ai = 0; ai < 2; ++ai)
; #pragma unroll
;             for (int m = 0; m < 4; ++m) { bf16_t* rowp = O + (size_t)(row0 + ai * HALF + m * 16) * ldc + col0;
; #pragma unroll
;                 for (int bj = 0; bj < 2; ++bj) *(u32x4*)(rowp + bj * HALF) = pack8(acc[ai][bj][m][0], acc[ai][bj][m][1]); }
; __device__ __forceinline__ void xcd_wait(const XcdBarrier& b, unsigned use) {
;     if (b.w0 != 0 && lane_id() == 0) {
;         unsigned* bar = b.bar;
;         XB_SPIN(xb_ld(&bar[XB_TOPGEN]) <= use, bar);
;         __builtin_amdgcn_fence(__ATOMIC_ACQUIRE, "agent");
;         asm volatile("s_waitcnt vmcnt(0)" ::: "memory");
;     }
;     __syncthreads();
.LBB0_558:
	v_lshl_add_u32 v130, s6, 8, v128
	v_ashrrev_i32_e32 v131, 31, v130
	v_or_b32_e32 v132, s97, v129
	v_lshlrev_b64 v[128:129], 12, v[130:131]
	v_lshl_add_u64 v[128:129], s[2:3], 0, v[128:129]
	v_lshlrev_b32_e32 v224, 1, v132
	v_mov_b32_e32 v225, 0
	v_lshl_add_u64 v[128:129], v[128:129], 0, v[224:225]
	v_cvt_pk_bf16_f32 v120, v120, v121
	v_cvt_pk_bf16_f32 v121, v122, v123
	v_cvt_pk_bf16_f32 v122, v112, v113
	v_cvt_pk_bf16_f32 v123, v114, v115
	global_store_dwordx4 v[128:129], v[120:123], off
	v_cvt_pk_bf16_f32 v112, v124, v125
	v_cvt_pk_bf16_f32 v113, v126, v127
	v_cvt_pk_bf16_f32 v114, v116, v117
	v_cvt_pk_bf16_f32 v115, v118, v119
	global_store_dwordx4 v[128:129], v[112:115], off offset:256
	v_cvt_pk_bf16_f32 v104, v104, v105
	v_cvt_pk_bf16_f32 v105, v106, v107
	v_cvt_pk_bf16_f32 v106, v96, v97
	v_cvt_pk_bf16_f32 v107, v98, v99
	s_mov_b64 s[0:1], 0x80000
	s_nop 0
	v_or_b32_e32 v112, 16, v130
	v_ashrrev_i32_e32 v113, 31, v112
	v_lshlrev_b64 v[112:113], 12, v[112:113]
	v_lshl_add_u64 v[112:113], s[2:3], 0, v[112:113]
	v_lshl_add_u64 v[112:113], v[112:113], 0, v[224:225]
	global_store_dwordx4 v[112:113], v[104:107], off
	v_cvt_pk_bf16_f32 v96, v108, v109
	v_cvt_pk_bf16_f32 v97, v110, v111
	v_cvt_pk_bf16_f32 v98, v100, v101
	v_cvt_pk_bf16_f32 v99, v102, v103
	global_store_dwordx4 v[112:113], v[96:99], off offset:256
	v_cvt_pk_bf16_f32 v88, v88, v89
	v_cvt_pk_bf16_f32 v89, v90, v91
	v_cvt_pk_bf16_f32 v90, v80, v81
	v_cvt_pk_bf16_f32 v91, v82, v83
	s_mov_b32 s42, 0
	s_nop 0
	v_or_b32_e32 v96, 32, v130
	v_ashrrev_i32_e32 v97, 31, v96
	v_lshlrev_b64 v[96:97], 12, v[96:97]
	v_lshl_add_u64 v[96:97], s[2:3], 0, v[96:97]
	v_lshl_add_u64 v[96:97], v[96:97], 0, v[224:225]
	global_store_dwordx4 v[96:97], v[88:91], off
	v_cvt_pk_bf16_f32 v80, v92, v93
	v_cvt_pk_bf16_f32 v81, v94, v95
	v_cvt_pk_bf16_f32 v82, v84, v85
	v_cvt_pk_bf16_f32 v83, v86, v87
	global_store_dwordx4 v[96:97], v[80:83], off offset:256
	v_cvt_pk_bf16_f32 v56, v56, v57
	v_cvt_pk_bf16_f32 v57, v58, v59
	v_cvt_pk_bf16_f32 v58, v48, v49
	v_cvt_pk_bf16_f32 v59, v50, v51
	s_nop 1
	v_or_b32_e32 v80, 48, v130
	v_ashrrev_i32_e32 v81, 31, v80
	v_lshlrev_b64 v[80:81], 12, v[80:81]
	v_lshl_add_u64 v[80:81], s[2:3], 0, v[80:81]
	v_lshl_add_u64 v[80:81], v[80:81], 0, v[224:225]
	global_store_dwordx4 v[80:81], v[56:59], off
	v_cvt_pk_bf16_f32 v48, v60, v61
	v_cvt_pk_bf16_f32 v49, v62, v63
	v_cvt_pk_bf16_f32 v50, v52, v53
	v_lshl_add_u64 v[52:53], v[128:129], 0, s[0:1]
	s_mov_b32 s0, 0x80000
	v_cvt_pk_bf16_f32 v51, v54, v55
	v_add_co_u32_e32 v54, vcc, s0, v128
	global_store_dwordx4 v[80:81], v[48:51], off offset:256
	s_nop 0
	v_addc_co_u32_e32 v55, vcc, 0, v129, vcc
	v_cvt_pk_bf16_f32 v48, v76, v77
	v_cvt_pk_bf16_f32 v49, v78, v79
	v_cvt_pk_bf16_f32 v50, v72, v73
	v_cvt_pk_bf16_f32 v51, v74, v75
	global_store_dwordx4 v[54:55], v[48:51], off
	s_mov_b64 s[0:1], 0x90000
	s_nop 0
	v_cvt_pk_bf16_f32 v48, v68, v69
	v_cvt_pk_bf16_f32 v49, v70, v71
	v_cvt_pk_bf16_f32 v50, v64, v65
	v_cvt_pk_bf16_f32 v51, v66, v67
	global_store_dwordx4 v[52:53], v[48:51], off offset:256
	v_cvt_pk_bf16_f32 v44, v44, v45
	v_cvt_pk_bf16_f32 v45, v46, v47
	v_cvt_pk_bf16_f32 v46, v36, v37
	v_cvt_pk_bf16_f32 v47, v38, v39
	s_nop 1
	v_lshl_add_u64 v[48:49], v[128:129], 0, s[0:1]
	s_mov_b32 s0, 0x90000
	v_add_co_u32_e32 v36, vcc, s0, v128
	s_mov_b64 s[0:1], 0xa0000
	s_nop 0
	v_addc_co_u32_e32 v37, vcc, 0, v129, vcc
	global_store_dwordx4 v[36:37], v[44:47], off
	v_cvt_pk_bf16_f32 v36, v40, v41
	v_cvt_pk_bf16_f32 v37, v42, v43
	v_cvt_pk_bf16_f32 v38, v32, v33
	v_lshl_add_u64 v[32:33], v[128:129], 0, s[0:1]
	s_mov_b32 s0, 0xa0000
	v_cvt_pk_bf16_f32 v39, v34, v35
	global_store_dwordx4 v[48:49], v[36:39], off offset:256
	v_cvt_pk_bf16_f32 v28, v28, v29
	v_cvt_pk_bf16_f32 v29, v30, v31
	v_cvt_pk_bf16_f32 v30, v20, v21
	v_add_co_u32_e32 v20, vcc, s0, v128
	s_mov_b64 s[0:1], 0xb0000
	s_nop 0
	v_addc_co_u32_e32 v21, vcc, 0, v129, vcc
	v_cvt_pk_bf16_f32 v31, v22, v23
	global_store_dwordx4 v[20:21], v[28:31], off
	v_cvt_pk_bf16_f32 v20, v24, v25
	v_cvt_pk_bf16_f32 v21, v26, v27
	v_cvt_pk_bf16_f32 v22, v16, v17
	v_lshl_add_u64 v[16:17], v[128:129], 0, s[0:1]
	s_mov_b32 s0, 0xb0000
	v_cvt_pk_bf16_f32 v23, v18, v19
	global_store_dwordx4 v[32:33], v[20:23], off offset:256
	v_cvt_pk_bf16_f32 v12, v12, v13
	v_cvt_pk_bf16_f32 v13, v14, v15
	v_cvt_pk_bf16_f32 v14, v4, v5
	v_add_co_u32_e32 v4, vcc, s0, v128
	v_cvt_pk_bf16_f32 v15, v6, v7
	s_nop 1
	v_addc_co_u32_e32 v5, vcc, 0, v129, vcc
	global_store_dwordx4 v[4:5], v[12:15], off
	v_cvt_pk_bf16_f32 v4, v8, v9
	v_cvt_pk_bf16_f32 v5, v10, v11
	v_cvt_pk_bf16_f32 v6, v0, v1
	v_cvt_pk_bf16_f32 v7, v2, v3
	global_store_dwordx4 v[16:17], v[4:7], off offset:256
	s_waitcnt vmcnt(0)
	s_and_b64 vcc, exec, s[94:95]
	s_barrier
	s_cbranch_vccnz .LBB0_575
	v_mbcnt_lo_u32_b32 v0, -1, 0
	v_mbcnt_hi_u32_b32 v0, -1, v0
	s_nop 0
	v_cmp_eq_u32_e32 vcc, 0, v0
	s_and_saveexec_b64 s[0:1], vcc
	s_cbranch_execz .LBB0_574
	v_readlane_b32 s6, v254, 19
	v_readlane_b32 s7, v254, 21
	s_add_i32 s6, s6, s7
	s_lshl_b32 s6, s6, 7
	s_add_u32 s6, s6, 0x7800
	v_mov_b32_e32 v0, s6
	global_load_dword v1, v0, s[52:53] sc1
	buffer_inv sc1
	s_waitcnt vmcnt(0)
	v_cmp_lt_u32_e32 vcc, 7, v1
	s_cbranch_vccnz .LBB0_574
	s_mov_b32 s13, 0x40000
